# v13 + retention accumulators initialised by first MFMA (C=0), attention PV transposed reads issued ahead, backward-direction stats reduced with DPP
# speedup vs baseline: 1.0176x; 1.0002x over previous
.LBB0_323:
	v_exp_f32_e32 v194, v112
	v_exp_f32_e32 v195, v80
	v_exp_f32_e32 v196, v113
	v_exp_f32_e32 v197, v81
	v_exp_f32_e32 v198, v114
	v_exp_f32_e32 v199, v82
	v_exp_f32_e32 v202, v115
	v_exp_f32_e32 v203, v83
	v_exp_f32_e32 v204, v116
	v_exp_f32_e32 v205, v84
	v_exp_f32_e32 v207, v85
	v_pk_add_f32 v[84:85], v[194:195], 0 op_sel_hi:[1,0]
	v_exp_f32_e32 v206, v117
	v_pk_add_f32 v[84:85], v[196:197], v[84:85]
	v_exp_f32_e32 v208, v118
	v_exp_f32_e32 v209, v86
	v_pk_add_f32 v[84:85], v[198:199], v[84:85]
	v_exp_f32_e32 v210, v119
	v_exp_f32_e32 v211, v87
	v_pk_add_f32 v[84:85], v[202:203], v[84:85]
	v_exp_f32_e32 v120, v120
	v_exp_f32_e32 v212, v121
	v_exp_f32_e32 v121, v88
	v_pk_add_f32 v[84:85], v[204:205], v[84:85]
	v_exp_f32_e32 v213, v89
	v_pk_add_f32 v[84:85], v[206:207], v[84:85]
	v_exp_f32_e32 v122, v122
	v_exp_f32_e32 v214, v123
	v_exp_f32_e32 v123, v90
	v_pk_add_f32 v[84:85], v[208:209], v[84:85]
	v_exp_f32_e32 v215, v91
	v_pk_add_f32 v[84:85], v[210:211], v[84:85]
	v_exp_f32_e32 v124, v124
	v_exp_f32_e32 v216, v125
	v_pk_add_f32 v[84:85], v[120:121], v[84:85]
	v_exp_f32_e32 v125, v92
	v_pk_add_f32 v[84:85], v[212:213], v[84:85]
	v_exp_f32_e32 v217, v93
	v_exp_f32_e32 v126, v126
	v_exp_f32_e32 v218, v127
	v_pk_add_f32 v[88:89], v[122:123], v[84:85]
	v_exp_f32_e32 v127, v94
	v_exp_f32_e32 v219, v95
	v_exp_f32_e32 v221, v64
	v_exp_f32_e32 v223, v65
	v_pk_add_f32 v[64:65], v[214:215], v[88:89]
	v_exp_f32_e32 v220, v96
	v_pk_add_f32 v[64:65], v[124:125], v[64:65]
	v_exp_f32_e32 v222, v97
	v_pk_add_f32 v[64:65], v[216:217], v[64:65]
	v_exp_f32_e32 v224, v98
	v_exp_f32_e32 v225, v66
	v_pk_add_f32 v[64:65], v[126:127], v[64:65]
	v_exp_f32_e32 v226, v99
	v_exp_f32_e32 v227, v67
	v_pk_add_f32 v[64:65], v[218:219], v[64:65]
	v_exp_f32_e32 v228, v100
	v_exp_f32_e32 v229, v68
	v_pk_add_f32 v[64:65], v[220:221], v[64:65]
	v_exp_f32_e32 v230, v101
	v_exp_f32_e32 v231, v69
	v_pk_add_f32 v[64:65], v[222:223], v[64:65]
	v_exp_f32_e32 v232, v102
	v_pk_add_f32 v[64:65], v[224:225], v[64:65]
	v_exp_f32_e32 v233, v70
	v_exp_f32_e32 v234, v103
	v_pk_add_f32 v[64:65], v[226:227], v[64:65]
	v_exp_f32_e32 v235, v71
	v_exp_f32_e32 v104, v104
	v_exp_f32_e32 v236, v105
	v_pk_add_f32 v[64:65], v[228:229], v[64:65]
	v_exp_f32_e32 v105, v72
	v_pk_add_f32 v[68:69], v[230:231], v[64:65]
	v_exp_f32_e32 v237, v73
	v_exp_f32_e32 v106, v106
	v_exp_f32_e32 v238, v107
	v_exp_f32_e32 v107, v74
	v_pk_add_f32 v[68:69], v[232:233], v[68:69]
	v_exp_f32_e32 v239, v75
	v_pk_add_f32 v[68:69], v[234:235], v[68:69]
	v_exp_f32_e32 v108, v108
	v_exp_f32_e32 v240, v109
	v_exp_f32_e32 v109, v76
	v_pk_add_f32 v[68:69], v[104:105], v[68:69]
	v_exp_f32_e32 v241, v77
	v_pk_add_f32 v[68:69], v[236:237], v[68:69]
	v_exp_f32_e32 v110, v110
	v_exp_f32_e32 v242, v111
	v_exp_f32_e32 v111, v78
	v_pk_add_f32 v[68:69], v[106:107], v[68:69]
	v_exp_f32_e32 v243, v79
	v_pk_add_f32 v[68:69], v[238:239], v[68:69]
	v_cvt_pk_bf16_f32 v116, v194, v196
	v_cvt_pk_bf16_f32 v117, v198, v202
	v_cvt_pk_bf16_f32 v118, v204, v206
	v_cvt_pk_bf16_f32 v119, v208, v210
	v_cvt_pk_bf16_f32 v112, v120, v212
	s_nop 0
	v_pk_add_f32 v[68:69], v[108:109], v[68:69]
	v_cvt_pk_bf16_f32 v113, v122, v214
	v_cvt_pk_bf16_f32 v114, v124, v216
	v_cvt_pk_bf16_f32 v115, v126, v218
	v_cvt_pk_bf16_f32 v100, v220, v222
	v_cvt_pk_bf16_f32 v101, v224, v226
	s_nop 0
	v_pk_add_f32 v[68:69], v[240:241], v[68:69]
	v_cvt_pk_bf16_f32 v102, v228, v230
	v_cvt_pk_bf16_f32 v103, v232, v234
	v_cvt_pk_bf16_f32 v96, v104, v236
	v_cvt_pk_bf16_f32 v97, v106, v238
	v_cvt_pk_bf16_f32 v98, v108, v240
	s_nop 0
	v_pk_add_f32 v[68:69], v[110:111], v[68:69]
	v_cvt_pk_bf16_f32 v99, v110, v242
	v_cvt_pk_bf16_f32 v80, v195, v197
	v_cvt_pk_bf16_f32 v81, v199, v203
	v_cvt_pk_bf16_f32 v82, v205, v207
	v_cvt_pk_bf16_f32 v83, v209, v211
	s_nop 0
	v_pk_add_f32 v[72:73], v[242:243], v[68:69]
	v_cvt_pk_bf16_f32 v84, v121, v213
	v_cvt_pk_bf16_f32 v85, v123, v215
	v_cvt_pk_bf16_f32 v86, v125, v217
	v_cvt_pk_bf16_f32 v87, v127, v219
	v_cvt_pk_bf16_f32 v64, v221, v223
	s_nop 0
	v_pk_add_f32 v[184:185], v[184:185], v[72:73]
	v_cvt_pk_bf16_f32 v65, v225, v227
	v_cvt_pk_bf16_f32 v66, v229, v231
	v_cvt_pk_bf16_f32 v67, v233, v235
	v_cvt_pk_bf16_f32 v68, v105, v237
	v_cvt_pk_bf16_f32 v69, v107, v239
	v_cvt_pk_bf16_f32 v70, v109, v241
	v_cvt_pk_bf16_f32 v71, v111, v243
	ds_read_b64_tr_b16 v[196:197], v191 offset:9216
	ds_read_b64_tr_b16 v[198:199], v191 offset:10368
	ds_read_b64_tr_b16 v[200:201], v191 offset:9280
	ds_read_b64_tr_b16 v[202:203], v191 offset:10432
	ds_read_b64_tr_b16 v[204:205], v191 offset:11520
	ds_read_b64_tr_b16 v[206:207], v191 offset:12672
	ds_read_b64_tr_b16 v[208:209], v191 offset:11584
	ds_read_b64_tr_b16 v[210:211], v191 offset:12736
	ds_read_b64_tr_b16 v[212:213], v191 offset:13824
	ds_read_b64_tr_b16 v[214:215], v191 offset:14976
	ds_read_b64_tr_b16 v[216:217], v191 offset:13888
	ds_read_b64_tr_b16 v[218:219], v191 offset:15040
	s_waitcnt lgkmcnt(10)
	v_mfma_f32_32x32x16_bf16 v[48:63], v[196:199], v[116:119], v[48:63]
	v_mfma_f32_32x32x16_bf16 v[16:31], v[196:199], v[80:83], v[16:31]
	ds_read_b64_tr_b16 v[220:221], v191 offset:16128
	ds_read_b64_tr_b16 v[222:223], v191 offset:17280
	s_waitcnt lgkmcnt(10)
	v_mfma_f32_32x32x16_bf16 v[32:47], v[200:203], v[116:119], v[32:47]
	v_mfma_f32_32x32x16_bf16 v[0:15], v[200:203], v[80:83], v[0:15]
	ds_read_b64_tr_b16 v[224:225], v191 offset:16192
	ds_read_b64_tr_b16 v[226:227], v191 offset:17344
	s_waitcnt lgkmcnt(10)
	v_mfma_f32_32x32x16_bf16 v[48:63], v[204:207], v[112:115], v[48:63]
	v_mfma_f32_32x32x16_bf16 v[16:31], v[204:207], v[84:87], v[16:31]
	s_waitcnt lgkmcnt(8)
	v_mfma_f32_32x32x16_bf16 v[32:47], v[208:211], v[112:115], v[32:47]
	v_mfma_f32_32x32x16_bf16 v[0:15], v[208:211], v[84:87], v[0:15]
	s_waitcnt lgkmcnt(6)
	v_mfma_f32_32x32x16_bf16 v[48:63], v[212:215], v[100:103], v[48:63]
	v_mfma_f32_32x32x16_bf16 v[16:31], v[212:215], v[64:67], v[16:31]
	s_waitcnt lgkmcnt(4)
	v_mfma_f32_32x32x16_bf16 v[0:15], v[216:219], v[64:67], v[0:15]
	v_mfma_f32_32x32x16_bf16 v[32:47], v[216:219], v[100:103], v[32:47]
	s_waitcnt lgkmcnt(2)
	v_mfma_f32_32x32x16_bf16 v[48:63], v[220:223], v[96:99], v[48:63]
	v_mfma_f32_32x32x16_bf16 v[16:31], v[220:223], v[68:71], v[16:31]
	s_waitcnt lgkmcnt(0)
	v_mfma_f32_32x32x16_bf16 v[32:47], v[224:227], v[96:99], v[32:47]
	v_mfma_f32_32x32x16_bf16 v[0:15], v[224:227], v[68:71], v[0:15]

.LBB0_914:
	v_lshl_add_u64 v[2:3], v[2:3], 1, s[18:19]
	global_load_dwordx4 v[176:179], v[2:3], off offset:256
	s_and_b64 vcc, exec, s[16:17]
	s_mov_b32 s33, 0
	s_waitcnt lgkmcnt(0)
	s_barrier
	v_sub_co_u32_e64 v1, s[14:15], s49, 1
	s_cbranch_vccnz .Lret_b0_ctx
	v_add_u32_e32 v14, 0x19800, v212
	s_and_b64 vcc, exec, s[2:3]
	s_cbranch_vccz .Lret_b0_c
	s_and_b64 vcc, exec, s[4:5]
	s_cbranch_vccz .Lret_b0_b
	ds_read_b128 v[2:5], v250
	ds_read_b128 v[6:9], v250 offset:8192
	ds_read_b128 v[10:13], v194
	v_xor_b32_e32 v15, 32, v250
	ds_read_b128 v[236:239], v15
	ds_read_b128 v[240:243], v15 offset:8192
	ds_read_b128 v[244:247], v194 offset:32
	v_xor_b32_e32 v15, 64, v250
	ds_read_b128 v[160:163], v15
	ds_read_b128 v[164:167], v15 offset:8192
	s_waitcnt lgkmcnt(5)
	v_mfma_f32_32x32x16_bf16 v[128:143], v[2:5], v[10:13], 0
	ds_read_b128 v[168:171], v194 offset:64
	v_mfma_f32_32x32x16_bf16 v[112:127], v[6:9], v[10:13], 0
	v_xor_b32_e32 v15, 0x60, v250
	ds_read_b128 v[2:5], v15
	ds_read_b128 v[6:9], v15 offset:8192
	s_waitcnt lgkmcnt(5)
	v_mfma_f32_32x32x16_bf16 v[128:143], v[236:239], v[244:247], v[128:143]
	ds_read_b128 v[10:13], v194 offset:96
	v_mfma_f32_32x32x16_bf16 v[112:127], v[240:243], v[244:247], v[112:127]
	v_xor_b32_e32 v15, 0x80, v250
	ds_read_b128 v[236:239], v15
	ds_read_b128 v[240:243], v15 offset:8192
	s_waitcnt lgkmcnt(5)
	v_mfma_f32_32x32x16_bf16 v[128:143], v[160:163], v[168:171], v[128:143]
	ds_read_b128 v[244:247], v194 offset:128
	v_mfma_f32_32x32x16_bf16 v[112:127], v[164:167], v[168:171], v[112:127]
	v_xor_b32_e32 v15, 0xa0, v250
	ds_read_b128 v[160:163], v15
	ds_read_b128 v[164:167], v15 offset:8192
	s_waitcnt lgkmcnt(5)
	v_mfma_f32_32x32x16_bf16 v[128:143], v[2:5], v[10:13], v[128:143]
	ds_read_b128 v[168:171], v194 offset:160
	v_mfma_f32_32x32x16_bf16 v[112:127], v[6:9], v[10:13], v[112:127]
	v_xor_b32_e32 v15, 0xc0, v250
	ds_read_b128 v[2:5], v15
	ds_read_b128 v[6:9], v15 offset:8192
	s_waitcnt lgkmcnt(5)
	v_mfma_f32_32x32x16_bf16 v[128:143], v[236:239], v[244:247], v[128:143]
	ds_read_b128 v[10:13], v194 offset:192
	v_mfma_f32_32x32x16_bf16 v[112:127], v[240:243], v[244:247], v[112:127]
	v_xor_b32_e32 v15, 0xe0, v250
	ds_read_b128 v[236:239], v15
	ds_read_b128 v[240:243], v15 offset:8192
	s_waitcnt lgkmcnt(5)
	v_mfma_f32_32x32x16_bf16 v[128:143], v[160:163], v[168:171], v[128:143]
	ds_read_b128 v[244:247], v194 offset:224
	v_mfma_f32_32x32x16_bf16 v[112:127], v[164:167], v[168:171], v[112:127]
	ds_read_b128 v[160:163], v14
	ds_read_b128 v[164:167], v195
	s_waitcnt lgkmcnt(5)
	v_mfma_f32_32x32x16_bf16 v[128:143], v[2:5], v[10:13], v[128:143]
	ds_read_b128 v[168:171], v195 offset:8704
	v_mfma_f32_32x32x16_bf16 v[112:127], v[6:9], v[10:13], v[112:127]
	ds_read_b128 v[2:5], v14 offset:32
	ds_read_b128 v[6:9], v195 offset:32
	s_waitcnt lgkmcnt(5)
	v_mfma_f32_32x32x16_bf16 v[128:143], v[236:239], v[244:247], v[128:143]
	ds_read_b128 v[10:13], v195 offset:8736
	v_mfma_f32_32x32x16_bf16 v[112:127], v[240:243], v[244:247], v[112:127]
	ds_read_b128 v[236:239], v14 offset:64
	ds_read_b128 v[240:243], v195 offset:64
	s_waitcnt lgkmcnt(5)
	v_mfma_f32_32x32x16_bf16 v[96:111], v[160:163], v[164:167], 0
	ds_read_b128 v[244:247], v195 offset:8768
	v_mfma_f32_32x32x16_bf16 v[80:95], v[160:163], v[168:171], 0
	ds_read_b128 v[160:163], v14 offset:96
	ds_read_b128 v[164:167], v195 offset:96
	s_waitcnt lgkmcnt(5)
	v_mfma_f32_32x32x16_bf16 v[96:111], v[2:5], v[6:9], v[96:111]
	ds_read_b128 v[168:171], v195 offset:8800
	v_mfma_f32_32x32x16_bf16 v[80:95], v[2:5], v[10:13], v[80:95]
	ds_read_b128 v[2:5], v14 offset:128
	ds_read_b128 v[6:9], v195 offset:128
	s_waitcnt lgkmcnt(5)
	v_mfma_f32_32x32x16_bf16 v[96:111], v[236:239], v[240:243], v[96:111]
	ds_read_b128 v[10:13], v195 offset:8832
	v_mfma_f32_32x32x16_bf16 v[80:95], v[236:239], v[244:247], v[80:95]
	ds_read_b128 v[236:239], v14 offset:160
	ds_read_b128 v[240:243], v195 offset:160
	s_waitcnt lgkmcnt(5)
	v_mfma_f32_32x32x16_bf16 v[96:111], v[160:163], v[164:167], v[96:111]
	ds_read_b128 v[244:247], v195 offset:8864
	v_mfma_f32_32x32x16_bf16 v[80:95], v[160:163], v[168:171], v[80:95]
	ds_read_b128 v[160:163], v14 offset:192
	ds_read_b128 v[164:167], v195 offset:192
	s_waitcnt lgkmcnt(5)
	v_mfma_f32_32x32x16_bf16 v[96:111], v[2:5], v[6:9], v[96:111]
	ds_read_b128 v[168:171], v195 offset:8896
	v_mfma_f32_32x32x16_bf16 v[80:95], v[2:5], v[10:13], v[80:95]
	ds_read_b128 v[2:5], v14 offset:224
	ds_read_b128 v[6:9], v195 offset:224
	s_waitcnt lgkmcnt(5)
	v_mfma_f32_32x32x16_bf16 v[96:111], v[236:239], v[240:243], v[96:111]
	ds_read_b128 v[10:13], v195 offset:8928
	v_mfma_f32_32x32x16_bf16 v[80:95], v[236:239], v[244:247], v[80:95]
	ds_read_b64_tr_b16 v[236:237], v251
	ds_read_b64_tr_b16 v[238:239], v252
	ds_read_b64_tr_b16 v[244:245], v235
	s_waitcnt lgkmcnt(6)
	v_mfma_f32_32x32x16_bf16 v[96:111], v[160:163], v[164:167], v[96:111]
	ds_read_b64_tr_b16 v[246:247], v255
	ds_read_b64_tr_b16 v[240:241], v253
	ds_read_b64_tr_b16 v[242:243], v200
	v_mfma_f32_32x32x16_bf16 v[80:95], v[160:163], v[168:171], v[80:95]
	ds_read_b64_tr_b16 v[160:161], v251 offset:4096
	ds_read_b64_tr_b16 v[162:163], v252 offset:4096
	ds_read_b64_tr_b16 v[168:169], v235 offset:4096
	s_waitcnt lgkmcnt(9)
	v_mfma_f32_32x32x16_bf16 v[96:111], v[2:5], v[6:9], v[96:111]
	ds_read_b64_tr_b16 v[170:171], v255 offset:4096
	ds_read_b64_tr_b16 v[164:165], v253 offset:4096
	ds_read_b64_tr_b16 v[166:167], v200 offset:4096
	v_mfma_f32_32x32x16_bf16 v[80:95], v[2:5], v[10:13], v[80:95]
	ds_read_b64_tr_b16 v[2:3], v251 offset:8192
	ds_read_b64_tr_b16 v[4:5], v252 offset:8192
	ds_read_b64_tr_b16 v[10:11], v235 offset:8192
	s_waitcnt lgkmcnt(9)
	v_mfma_f32_32x32x16_bf16 v[64:79], v[236:239], v[244:247], v[64:79]
	ds_read_b64_tr_b16 v[12:13], v255 offset:8192
	ds_read_b64_tr_b16 v[6:7], v253 offset:8192
	ds_read_b64_tr_b16 v[8:9], v200 offset:8192
	v_mfma_f32_32x32x16_bf16 v[48:63], v[240:243], v[244:247], v[48:63]
	ds_read_b64_tr_b16 v[236:237], v251 offset:12288
	ds_read_b64_tr_b16 v[238:239], v252 offset:12288
	ds_read_b64_tr_b16 v[244:245], v235 offset:12288
	s_waitcnt lgkmcnt(9)
	v_mfma_f32_32x32x16_bf16 v[64:79], v[160:163], v[168:171], v[64:79]
	ds_read_b64_tr_b16 v[246:247], v255 offset:12288
	ds_read_b64_tr_b16 v[240:241], v253 offset:12288
	ds_read_b64_tr_b16 v[242:243], v200 offset:12288
	v_mfma_f32_32x32x16_bf16 v[48:63], v[164:167], v[168:171], v[48:63]
	ds_read_b64_tr_b16 v[160:161], v251 offset:16384
	ds_read_b64_tr_b16 v[162:163], v252 offset:16384
	ds_read_b64_tr_b16 v[168:169], v235 offset:16384
	s_waitcnt lgkmcnt(9)
	v_mfma_f32_32x32x16_bf16 v[64:79], v[2:5], v[10:13], v[64:79]
	ds_read_b64_tr_b16 v[170:171], v255 offset:16384
	ds_read_b64_tr_b16 v[164:165], v253 offset:16384
	ds_read_b64_tr_b16 v[166:167], v200 offset:16384
	v_mfma_f32_32x32x16_bf16 v[48:63], v[6:9], v[10:13], v[48:63]
	ds_read_b64_tr_b16 v[2:3], v251 offset:20480
	ds_read_b64_tr_b16 v[4:5], v252 offset:20480
	ds_read_b64_tr_b16 v[10:11], v235 offset:20480
	s_waitcnt lgkmcnt(9)
	v_mfma_f32_32x32x16_bf16 v[64:79], v[236:239], v[244:247], v[64:79]
	ds_read_b64_tr_b16 v[12:13], v255 offset:20480
	ds_read_b64_tr_b16 v[6:7], v253 offset:20480
	ds_read_b64_tr_b16 v[8:9], v200 offset:20480
	v_mfma_f32_32x32x16_bf16 v[48:63], v[240:243], v[244:247], v[48:63]
	ds_read_b64_tr_b16 v[236:237], v251 offset:24576
	ds_read_b64_tr_b16 v[238:239], v252 offset:24576
	ds_read_b64_tr_b16 v[244:245], v235 offset:24576
	s_waitcnt lgkmcnt(9)
	v_mfma_f32_32x32x16_bf16 v[64:79], v[160:163], v[168:171], v[64:79]
	ds_read_b64_tr_b16 v[246:247], v255 offset:24576
	ds_read_b64_tr_b16 v[240:241], v253 offset:24576
	ds_read_b64_tr_b16 v[242:243], v200 offset:24576
	v_mfma_f32_32x32x16_bf16 v[48:63], v[164:167], v[168:171], v[48:63]
	ds_read_b64_tr_b16 v[160:161], v251 offset:28672
	ds_read_b64_tr_b16 v[162:163], v252 offset:28672
	ds_read_b64_tr_b16 v[168:169], v235 offset:28672
	s_waitcnt lgkmcnt(9)
	v_mfma_f32_32x32x16_bf16 v[64:79], v[2:5], v[10:13], v[64:79]
	ds_read_b64_tr_b16 v[170:171], v255 offset:28672
	ds_read_b64_tr_b16 v[164:165], v253 offset:28672
	ds_read_b64_tr_b16 v[166:167], v200 offset:28672
	v_mfma_f32_32x32x16_bf16 v[48:63], v[6:9], v[10:13], v[48:63]
	s_waitcnt lgkmcnt(6)
	v_mfma_f32_32x32x16_bf16 v[64:79], v[236:239], v[244:247], v[64:79]
	v_mfma_f32_32x32x16_bf16 v[48:63], v[240:243], v[244:247], v[48:63]
	s_waitcnt lgkmcnt(0)
	v_mfma_f32_32x32x16_bf16 v[64:79], v[160:163], v[168:171], v[64:79]
	v_mfma_f32_32x32x16_bf16 v[48:63], v[164:167], v[168:171], v[48:63]
	s_branch .Lret_b0_end
.Lret_b0_b:
	v_mov_b32_e32 v112, 0
	v_mov_b32_e32 v113, 0
	v_mov_b32_e32 v114, 0
	v_mov_b32_e32 v115, 0
	v_mov_b32_e32 v116, 0
	v_mov_b32_e32 v117, 0
	v_mov_b32_e32 v118, 0
	v_mov_b32_e32 v119, 0
	v_mov_b32_e32 v120, 0
	v_mov_b32_e32 v121, 0
	v_mov_b32_e32 v122, 0
	v_mov_b32_e32 v123, 0
	v_mov_b32_e32 v124, 0
	v_mov_b32_e32 v125, 0
	v_mov_b32_e32 v126, 0
	v_mov_b32_e32 v127, 0
	ds_read_b128 v[2:5], v250
	ds_read_b128 v[10:13], v194
	v_xor_b32_e32 v15, 32, v250
	ds_read_b128 v[236:239], v15
	ds_read_b128 v[244:247], v194 offset:32
	v_xor_b32_e32 v15, 64, v250
	ds_read_b128 v[160:163], v15
	s_waitcnt lgkmcnt(3)
	v_mfma_f32_32x32x16_bf16 v[128:143], v[2:5], v[10:13], 0
	ds_read_b128 v[168:171], v194 offset:64
	v_xor_b32_e32 v15, 0x60, v250
	ds_read_b128 v[2:5], v15
	s_waitcnt lgkmcnt(3)
	v_mfma_f32_32x32x16_bf16 v[128:143], v[236:239], v[244:247], v[128:143]
	ds_read_b128 v[10:13], v194 offset:96
	v_xor_b32_e32 v15, 0x80, v250
	ds_read_b128 v[236:239], v15
	s_waitcnt lgkmcnt(3)
	v_mfma_f32_32x32x16_bf16 v[128:143], v[160:163], v[168:171], v[128:143]
	ds_read_b128 v[244:247], v194 offset:128
	v_xor_b32_e32 v15, 0xa0, v250
	ds_read_b128 v[160:163], v15
	s_waitcnt lgkmcnt(3)
	v_mfma_f32_32x32x16_bf16 v[128:143], v[2:5], v[10:13], v[128:143]
	ds_read_b128 v[168:171], v194 offset:160
	v_xor_b32_e32 v15, 0xc0, v250
	ds_read_b128 v[2:5], v15
	s_waitcnt lgkmcnt(3)
	v_mfma_f32_32x32x16_bf16 v[128:143], v[236:239], v[244:247], v[128:143]
	ds_read_b128 v[10:13], v194 offset:192
	v_xor_b32_e32 v15, 0xe0, v250
	ds_read_b128 v[236:239], v15
	s_waitcnt lgkmcnt(3)
	v_mfma_f32_32x32x16_bf16 v[128:143], v[160:163], v[168:171], v[128:143]
	ds_read_b128 v[244:247], v194 offset:224
	ds_read_b128 v[160:163], v14
	ds_read_b128 v[164:167], v195
	s_waitcnt lgkmcnt(4)
	v_mfma_f32_32x32x16_bf16 v[128:143], v[2:5], v[10:13], v[128:143]
	ds_read_b128 v[168:171], v195 offset:8704
	ds_read_b128 v[2:5], v14 offset:32
	ds_read_b128 v[6:9], v195 offset:32
	s_waitcnt lgkmcnt(5)
	v_mfma_f32_32x32x16_bf16 v[128:143], v[236:239], v[244:247], v[128:143]
	ds_read_b128 v[10:13], v195 offset:8736
	ds_read_b128 v[236:239], v14 offset:64
	ds_read_b128 v[240:243], v195 offset:64
	s_waitcnt lgkmcnt(5)
	v_mfma_f32_32x32x16_bf16 v[96:111], v[160:163], v[164:167], 0
	ds_read_b128 v[244:247], v195 offset:8768
	v_mfma_f32_32x32x16_bf16 v[80:95], v[160:163], v[168:171], 0
	ds_read_b128 v[160:163], v14 offset:96
	ds_read_b128 v[164:167], v195 offset:96
	s_waitcnt lgkmcnt(5)
	v_mfma_f32_32x32x16_bf16 v[96:111], v[2:5], v[6:9], v[96:111]
	ds_read_b128 v[168:171], v195 offset:8800
	v_mfma_f32_32x32x16_bf16 v[80:95], v[2:5], v[10:13], v[80:95]
	ds_read_b128 v[2:5], v14 offset:128
	ds_read_b128 v[6:9], v195 offset:128
	s_waitcnt lgkmcnt(5)
	v_mfma_f32_32x32x16_bf16 v[96:111], v[236:239], v[240:243], v[96:111]
	ds_read_b128 v[10:13], v195 offset:8832
	v_mfma_f32_32x32x16_bf16 v[80:95], v[236:239], v[244:247], v[80:95]
	ds_read_b128 v[236:239], v14 offset:160
	ds_read_b128 v[240:243], v195 offset:160
	s_waitcnt lgkmcnt(5)
	v_mfma_f32_32x32x16_bf16 v[96:111], v[160:163], v[164:167], v[96:111]
	ds_read_b128 v[244:247], v195 offset:8864
	v_mfma_f32_32x32x16_bf16 v[80:95], v[160:163], v[168:171], v[80:95]
	ds_read_b128 v[160:163], v14 offset:192
	ds_read_b128 v[164:167], v195 offset:192
	s_waitcnt lgkmcnt(5)
	v_mfma_f32_32x32x16_bf16 v[96:111], v[2:5], v[6:9], v[96:111]
	ds_read_b128 v[168:171], v195 offset:8896
	v_mfma_f32_32x32x16_bf16 v[80:95], v[2:5], v[10:13], v[80:95]
	ds_read_b128 v[2:5], v14 offset:224
	ds_read_b128 v[6:9], v195 offset:224
	s_waitcnt lgkmcnt(5)
	v_mfma_f32_32x32x16_bf16 v[96:111], v[236:239], v[240:243], v[96:111]
	ds_read_b128 v[10:13], v195 offset:8928
	v_mfma_f32_32x32x16_bf16 v[80:95], v[236:239], v[244:247], v[80:95]
	ds_read_b64_tr_b16 v[236:237], v251
	ds_read_b64_tr_b16 v[238:239], v252
	ds_read_b64_tr_b16 v[244:245], v235
	s_waitcnt lgkmcnt(6)
	v_mfma_f32_32x32x16_bf16 v[96:111], v[160:163], v[164:167], v[96:111]
	ds_read_b64_tr_b16 v[246:247], v255
	ds_read_b64_tr_b16 v[240:241], v253
	ds_read_b64_tr_b16 v[242:243], v200
	v_mfma_f32_32x32x16_bf16 v[80:95], v[160:163], v[168:171], v[80:95]
	ds_read_b64_tr_b16 v[160:161], v251 offset:4096
	ds_read_b64_tr_b16 v[162:163], v252 offset:4096
	ds_read_b64_tr_b16 v[168:169], v235 offset:4096
	s_waitcnt lgkmcnt(9)
	v_mfma_f32_32x32x16_bf16 v[96:111], v[2:5], v[6:9], v[96:111]
	ds_read_b64_tr_b16 v[170:171], v255 offset:4096
	ds_read_b64_tr_b16 v[164:165], v253 offset:4096
	ds_read_b64_tr_b16 v[166:167], v200 offset:4096
	v_mfma_f32_32x32x16_bf16 v[80:95], v[2:5], v[10:13], v[80:95]
	ds_read_b64_tr_b16 v[2:3], v251 offset:8192
	ds_read_b64_tr_b16 v[4:5], v252 offset:8192
	ds_read_b64_tr_b16 v[10:11], v235 offset:8192
	s_waitcnt lgkmcnt(9)
	v_mfma_f32_32x32x16_bf16 v[64:79], v[236:239], v[244:247], v[64:79]
	ds_read_b64_tr_b16 v[12:13], v255 offset:8192
	ds_read_b64_tr_b16 v[6:7], v253 offset:8192
	ds_read_b64_tr_b16 v[8:9], v200 offset:8192
	v_mfma_f32_32x32x16_bf16 v[48:63], v[240:243], v[244:247], v[48:63]
	ds_read_b64_tr_b16 v[236:237], v251 offset:12288
	ds_read_b64_tr_b16 v[238:239], v252 offset:12288
	ds_read_b64_tr_b16 v[244:245], v235 offset:12288
	s_waitcnt lgkmcnt(9)
	v_mfma_f32_32x32x16_bf16 v[64:79], v[160:163], v[168:171], v[64:79]
	ds_read_b64_tr_b16 v[246:247], v255 offset:12288
	ds_read_b64_tr_b16 v[240:241], v253 offset:12288
	ds_read_b64_tr_b16 v[242:243], v200 offset:12288
	v_mfma_f32_32x32x16_bf16 v[48:63], v[164:167], v[168:171], v[48:63]
	ds_read_b64_tr_b16 v[160:161], v251 offset:16384
	ds_read_b64_tr_b16 v[162:163], v252 offset:16384
	ds_read_b64_tr_b16 v[168:169], v235 offset:16384
	s_waitcnt lgkmcnt(9)
	v_mfma_f32_32x32x16_bf16 v[64:79], v[2:5], v[10:13], v[64:79]
	ds_read_b64_tr_b16 v[170:171], v255 offset:16384
	ds_read_b64_tr_b16 v[164:165], v253 offset:16384
	ds_read_b64_tr_b16 v[166:167], v200 offset:16384
	v_mfma_f32_32x32x16_bf16 v[48:63], v[6:9], v[10:13], v[48:63]
	ds_read_b64_tr_b16 v[2:3], v251 offset:20480
	ds_read_b64_tr_b16 v[4:5], v252 offset:20480
	ds_read_b64_tr_b16 v[10:11], v235 offset:20480
	s_waitcnt lgkmcnt(9)
	v_mfma_f32_32x32x16_bf16 v[64:79], v[236:239], v[244:247], v[64:79]
	ds_read_b64_tr_b16 v[12:13], v255 offset:20480
	ds_read_b64_tr_b16 v[6:7], v253 offset:20480
	ds_read_b64_tr_b16 v[8:9], v200 offset:20480
	v_mfma_f32_32x32x16_bf16 v[48:63], v[240:243], v[244:247], v[48:63]
	ds_read_b64_tr_b16 v[236:237], v251 offset:24576
	ds_read_b64_tr_b16 v[238:239], v252 offset:24576
	ds_read_b64_tr_b16 v[244:245], v235 offset:24576
	s_waitcnt lgkmcnt(9)
	v_mfma_f32_32x32x16_bf16 v[64:79], v[160:163], v[168:171], v[64:79]
	ds_read_b64_tr_b16 v[246:247], v255 offset:24576
	ds_read_b64_tr_b16 v[240:241], v253 offset:24576
	ds_read_b64_tr_b16 v[242:243], v200 offset:24576
	v_mfma_f32_32x32x16_bf16 v[48:63], v[164:167], v[168:171], v[48:63]
	ds_read_b64_tr_b16 v[160:161], v251 offset:28672
	ds_read_b64_tr_b16 v[162:163], v252 offset:28672
	ds_read_b64_tr_b16 v[168:169], v235 offset:28672
	s_waitcnt lgkmcnt(9)
	v_mfma_f32_32x32x16_bf16 v[64:79], v[2:5], v[10:13], v[64:79]
	ds_read_b64_tr_b16 v[170:171], v255 offset:28672
	ds_read_b64_tr_b16 v[164:165], v253 offset:28672
	ds_read_b64_tr_b16 v[166:167], v200 offset:28672
	v_mfma_f32_32x32x16_bf16 v[48:63], v[6:9], v[10:13], v[48:63]
	s_waitcnt lgkmcnt(6)
	v_mfma_f32_32x32x16_bf16 v[64:79], v[236:239], v[244:247], v[64:79]
	v_mfma_f32_32x32x16_bf16 v[48:63], v[240:243], v[244:247], v[48:63]
	s_waitcnt lgkmcnt(0)
	v_mfma_f32_32x32x16_bf16 v[64:79], v[160:163], v[168:171], v[64:79]
	v_mfma_f32_32x32x16_bf16 v[48:63], v[164:167], v[168:171], v[48:63]
	s_branch .Lret_b0_end
.Lret_b0_c:
	v_mov_b32_e32 v112, 0
	v_mov_b32_e32 v113, 0
	v_mov_b32_e32 v114, 0
	v_mov_b32_e32 v115, 0
	v_mov_b32_e32 v116, 0
	v_mov_b32_e32 v117, 0
	v_mov_b32_e32 v118, 0
	v_mov_b32_e32 v119, 0
	v_mov_b32_e32 v120, 0
	v_mov_b32_e32 v121, 0
	v_mov_b32_e32 v122, 0
	v_mov_b32_e32 v123, 0
	v_mov_b32_e32 v124, 0
	v_mov_b32_e32 v125, 0
	v_mov_b32_e32 v126, 0
	v_mov_b32_e32 v127, 0
	v_mov_b32_e32 v128, 0
	v_mov_b32_e32 v129, 0
	v_mov_b32_e32 v130, 0
	v_mov_b32_e32 v131, 0
	v_mov_b32_e32 v132, 0
	v_mov_b32_e32 v133, 0
	v_mov_b32_e32 v134, 0
	v_mov_b32_e32 v135, 0
	v_mov_b32_e32 v136, 0
	v_mov_b32_e32 v137, 0
	v_mov_b32_e32 v138, 0
	v_mov_b32_e32 v139, 0
	v_mov_b32_e32 v140, 0
	v_mov_b32_e32 v141, 0
	v_mov_b32_e32 v142, 0
	v_mov_b32_e32 v143, 0
	ds_read_b128 v[2:5], v14
	ds_read_b128 v[6:9], v195
	ds_read_b128 v[10:13], v195 offset:8704
	ds_read_b128 v[236:239], v14 offset:32
	ds_read_b128 v[240:243], v195 offset:32
	ds_read_b128 v[244:247], v195 offset:8736
	ds_read_b128 v[160:163], v14 offset:64
	ds_read_b128 v[164:167], v195 offset:64
	s_waitcnt lgkmcnt(5)
	v_mfma_f32_32x32x16_bf16 v[96:111], v[2:5], v[6:9], 0
	ds_read_b128 v[168:171], v195 offset:8768
	v_mfma_f32_32x32x16_bf16 v[80:95], v[2:5], v[10:13], 0
	ds_read_b128 v[2:5], v14 offset:96
	ds_read_b128 v[6:9], v195 offset:96
	s_waitcnt lgkmcnt(5)
	v_mfma_f32_32x32x16_bf16 v[96:111], v[236:239], v[240:243], v[96:111]
	ds_read_b128 v[10:13], v195 offset:8800
	v_mfma_f32_32x32x16_bf16 v[80:95], v[236:239], v[244:247], v[80:95]
	ds_read_b128 v[236:239], v14 offset:128
	ds_read_b128 v[240:243], v195 offset:128
	s_waitcnt lgkmcnt(5)
	v_mfma_f32_32x32x16_bf16 v[96:111], v[160:163], v[164:167], v[96:111]
	ds_read_b128 v[244:247], v195 offset:8832
	v_mfma_f32_32x32x16_bf16 v[80:95], v[160:163], v[168:171], v[80:95]
	ds_read_b128 v[160:163], v14 offset:160
	ds_read_b128 v[164:167], v195 offset:160
	s_waitcnt lgkmcnt(5)
	v_mfma_f32_32x32x16_bf16 v[96:111], v[2:5], v[6:9], v[96:111]
	ds_read_b128 v[168:171], v195 offset:8864
	v_mfma_f32_32x32x16_bf16 v[80:95], v[2:5], v[10:13], v[80:95]
	ds_read_b128 v[2:5], v14 offset:192
	ds_read_b128 v[6:9], v195 offset:192
	s_waitcnt lgkmcnt(5)
	v_mfma_f32_32x32x16_bf16 v[96:111], v[236:239], v[240:243], v[96:111]
	ds_read_b128 v[10:13], v195 offset:8896
	v_mfma_f32_32x32x16_bf16 v[80:95], v[236:239], v[244:247], v[80:95]
	ds_read_b128 v[236:239], v14 offset:224
	ds_read_b128 v[240:243], v195 offset:224
	s_waitcnt lgkmcnt(5)
	v_mfma_f32_32x32x16_bf16 v[96:111], v[160:163], v[164:167], v[96:111]
	ds_read_b128 v[244:247], v195 offset:8928
	v_mfma_f32_32x32x16_bf16 v[80:95], v[160:163], v[168:171], v[80:95]
	ds_read_b64_tr_b16 v[160:161], v251
	ds_read_b64_tr_b16 v[162:163], v252
	ds_read_b64_tr_b16 v[168:169], v235
	s_waitcnt lgkmcnt(6)
	v_mfma_f32_32x32x16_bf16 v[96:111], v[2:5], v[6:9], v[96:111]
	ds_read_b64_tr_b16 v[170:171], v255
	ds_read_b64_tr_b16 v[164:165], v253
	ds_read_b64_tr_b16 v[166:167], v200
	v_mfma_f32_32x32x16_bf16 v[80:95], v[2:5], v[10:13], v[80:95]
	ds_read_b64_tr_b16 v[2:3], v251 offset:4096
	ds_read_b64_tr_b16 v[4:5], v252 offset:4096
	ds_read_b64_tr_b16 v[10:11], v235 offset:4096
	s_waitcnt lgkmcnt(9)
	v_mfma_f32_32x32x16_bf16 v[96:111], v[236:239], v[240:243], v[96:111]
	ds_read_b64_tr_b16 v[12:13], v255 offset:4096
	ds_read_b64_tr_b16 v[6:7], v253 offset:4096
	ds_read_b64_tr_b16 v[8:9], v200 offset:4096
	v_mfma_f32_32x32x16_bf16 v[80:95], v[236:239], v[244:247], v[80:95]
	ds_read_b64_tr_b16 v[236:237], v251 offset:8192
	ds_read_b64_tr_b16 v[238:239], v252 offset:8192
	ds_read_b64_tr_b16 v[244:245], v235 offset:8192
	s_waitcnt lgkmcnt(9)
	v_mfma_f32_32x32x16_bf16 v[64:79], v[160:163], v[168:171], v[64:79]
	ds_read_b64_tr_b16 v[246:247], v255 offset:8192
	ds_read_b64_tr_b16 v[240:241], v253 offset:8192
	ds_read_b64_tr_b16 v[242:243], v200 offset:8192
	v_mfma_f32_32x32x16_bf16 v[48:63], v[164:167], v[168:171], v[48:63]
	ds_read_b64_tr_b16 v[160:161], v251 offset:12288
	ds_read_b64_tr_b16 v[162:163], v252 offset:12288
	ds_read_b64_tr_b16 v[168:169], v235 offset:12288
	s_waitcnt lgkmcnt(9)
	v_mfma_f32_32x32x16_bf16 v[64:79], v[2:5], v[10:13], v[64:79]
	ds_read_b64_tr_b16 v[170:171], v255 offset:12288
	ds_read_b64_tr_b16 v[164:165], v253 offset:12288
	ds_read_b64_tr_b16 v[166:167], v200 offset:12288
	v_mfma_f32_32x32x16_bf16 v[48:63], v[6:9], v[10:13], v[48:63]
	ds_read_b64_tr_b16 v[2:3], v251 offset:16384
	ds_read_b64_tr_b16 v[4:5], v252 offset:16384
	ds_read_b64_tr_b16 v[10:11], v235 offset:16384
	s_waitcnt lgkmcnt(9)
	v_mfma_f32_32x32x16_bf16 v[64:79], v[236:239], v[244:247], v[64:79]
	ds_read_b64_tr_b16 v[12:13], v255 offset:16384
	ds_read_b64_tr_b16 v[6:7], v253 offset:16384
	ds_read_b64_tr_b16 v[8:9], v200 offset:16384
	v_mfma_f32_32x32x16_bf16 v[48:63], v[240:243], v[244:247], v[48:63]
	ds_read_b64_tr_b16 v[236:237], v251 offset:20480
	ds_read_b64_tr_b16 v[238:239], v252 offset:20480
	ds_read_b64_tr_b16 v[244:245], v235 offset:20480
	s_waitcnt lgkmcnt(9)
	v_mfma_f32_32x32x16_bf16 v[64:79], v[160:163], v[168:171], v[64:79]
	ds_read_b64_tr_b16 v[246:247], v255 offset:20480
	ds_read_b64_tr_b16 v[240:241], v253 offset:20480
	ds_read_b64_tr_b16 v[242:243], v200 offset:20480
	v_mfma_f32_32x32x16_bf16 v[48:63], v[164:167], v[168:171], v[48:63]
	ds_read_b64_tr_b16 v[160:161], v251 offset:24576
	ds_read_b64_tr_b16 v[162:163], v252 offset:24576
	ds_read_b64_tr_b16 v[168:169], v235 offset:24576
	s_waitcnt lgkmcnt(9)
	v_mfma_f32_32x32x16_bf16 v[64:79], v[2:5], v[10:13], v[64:79]
	ds_read_b64_tr_b16 v[170:171], v255 offset:24576
	ds_read_b64_tr_b16 v[164:165], v253 offset:24576
	ds_read_b64_tr_b16 v[166:167], v200 offset:24576
	v_mfma_f32_32x32x16_bf16 v[48:63], v[6:9], v[10:13], v[48:63]
	ds_read_b64_tr_b16 v[2:3], v251 offset:28672
	ds_read_b64_tr_b16 v[4:5], v252 offset:28672
	ds_read_b64_tr_b16 v[10:11], v235 offset:28672
	s_waitcnt lgkmcnt(9)
	v_mfma_f32_32x32x16_bf16 v[64:79], v[236:239], v[244:247], v[64:79]
	ds_read_b64_tr_b16 v[12:13], v255 offset:28672
	ds_read_b64_tr_b16 v[6:7], v253 offset:28672
	ds_read_b64_tr_b16 v[8:9], v200 offset:28672
	v_mfma_f32_32x32x16_bf16 v[48:63], v[240:243], v[244:247], v[48:63]
	s_waitcnt lgkmcnt(6)
	v_mfma_f32_32x32x16_bf16 v[64:79], v[160:163], v[168:171], v[64:79]
	v_mfma_f32_32x32x16_bf16 v[48:63], v[164:167], v[168:171], v[48:63]
	s_waitcnt lgkmcnt(0)
	v_mfma_f32_32x32x16_bf16 v[64:79], v[2:5], v[10:13], v[64:79]
	v_mfma_f32_32x32x16_bf16 v[48:63], v[6:9], v[10:13], v[48:63]
	s_branch .Lret_b0_end
.Lret_b0_ctx:
	ds_read_b64_tr_b16 v[2:3], v251
	ds_read_b64_tr_b16 v[4:5], v252
	ds_read_b64_tr_b16 v[10:11], v235
	ds_read_b64_tr_b16 v[12:13], v255
	ds_read_b64_tr_b16 v[6:7], v253
	ds_read_b64_tr_b16 v[8:9], v200
	ds_read_b64_tr_b16 v[236:237], v251 offset:4096
	ds_read_b64_tr_b16 v[238:239], v252 offset:4096
	ds_read_b64_tr_b16 v[244:245], v235 offset:4096
	ds_read_b64_tr_b16 v[246:247], v255 offset:4096
	ds_read_b64_tr_b16 v[240:241], v253 offset:4096
	ds_read_b64_tr_b16 v[242:243], v200 offset:4096
	ds_read_b64_tr_b16 v[160:161], v251 offset:8192
	ds_read_b64_tr_b16 v[162:163], v252 offset:8192
	ds_read_b64_tr_b16 v[168:169], v235 offset:8192
	s_waitcnt lgkmcnt(9)
	v_mfma_f32_32x32x16_bf16 v[64:79], v[2:5], v[10:13], v[64:79]
	ds_read_b64_tr_b16 v[170:171], v255 offset:8192
	ds_read_b64_tr_b16 v[164:165], v253 offset:8192
	ds_read_b64_tr_b16 v[166:167], v200 offset:8192
	v_mfma_f32_32x32x16_bf16 v[48:63], v[6:9], v[10:13], v[48:63]
	ds_read_b64_tr_b16 v[2:3], v251 offset:12288
	ds_read_b64_tr_b16 v[4:5], v252 offset:12288
	ds_read_b64_tr_b16 v[10:11], v235 offset:12288
	s_waitcnt lgkmcnt(9)
	v_mfma_f32_32x32x16_bf16 v[64:79], v[236:239], v[244:247], v[64:79]
	ds_read_b64_tr_b16 v[12:13], v255 offset:12288
	ds_read_b64_tr_b16 v[6:7], v253 offset:12288
	ds_read_b64_tr_b16 v[8:9], v200 offset:12288
	v_mfma_f32_32x32x16_bf16 v[48:63], v[240:243], v[244:247], v[48:63]
	ds_read_b64_tr_b16 v[236:237], v251 offset:16384
	ds_read_b64_tr_b16 v[238:239], v252 offset:16384
	ds_read_b64_tr_b16 v[244:245], v235 offset:16384
	s_waitcnt lgkmcnt(9)
	v_mfma_f32_32x32x16_bf16 v[64:79], v[160:163], v[168:171], v[64:79]
	ds_read_b64_tr_b16 v[246:247], v255 offset:16384
	ds_read_b64_tr_b16 v[240:241], v253 offset:16384
	ds_read_b64_tr_b16 v[242:243], v200 offset:16384
	v_mfma_f32_32x32x16_bf16 v[48:63], v[164:167], v[168:171], v[48:63]
	ds_read_b64_tr_b16 v[160:161], v251 offset:20480
	ds_read_b64_tr_b16 v[162:163], v252 offset:20480
	ds_read_b64_tr_b16 v[168:169], v235 offset:20480
	s_waitcnt lgkmcnt(9)
	v_mfma_f32_32x32x16_bf16 v[64:79], v[2:5], v[10:13], v[64:79]
	ds_read_b64_tr_b16 v[170:171], v255 offset:20480
	ds_read_b64_tr_b16 v[164:165], v253 offset:20480
	ds_read_b64_tr_b16 v[166:167], v200 offset:20480
	v_mfma_f32_32x32x16_bf16 v[48:63], v[6:9], v[10:13], v[48:63]
	ds_read_b64_tr_b16 v[2:3], v251 offset:24576
	ds_read_b64_tr_b16 v[4:5], v252 offset:24576
	ds_read_b64_tr_b16 v[10:11], v235 offset:24576
	s_waitcnt lgkmcnt(9)
	v_mfma_f32_32x32x16_bf16 v[64:79], v[236:239], v[244:247], v[64:79]
	ds_read_b64_tr_b16 v[12:13], v255 offset:24576
	ds_read_b64_tr_b16 v[6:7], v253 offset:24576
	ds_read_b64_tr_b16 v[8:9], v200 offset:24576
	v_mfma_f32_32x32x16_bf16 v[48:63], v[240:243], v[244:247], v[48:63]
	ds_read_b64_tr_b16 v[236:237], v251 offset:28672
	ds_read_b64_tr_b16 v[238:239], v252 offset:28672
	ds_read_b64_tr_b16 v[244:245], v235 offset:28672
	s_waitcnt lgkmcnt(9)
	v_mfma_f32_32x32x16_bf16 v[64:79], v[160:163], v[168:171], v[64:79]
	ds_read_b64_tr_b16 v[246:247], v255 offset:28672
	ds_read_b64_tr_b16 v[240:241], v253 offset:28672
	ds_read_b64_tr_b16 v[242:243], v200 offset:28672
	v_mfma_f32_32x32x16_bf16 v[48:63], v[164:167], v[168:171], v[48:63]
	s_waitcnt lgkmcnt(6)
	v_mfma_f32_32x32x16_bf16 v[64:79], v[2:5], v[10:13], v[64:79]
	v_mfma_f32_32x32x16_bf16 v[48:63], v[6:9], v[10:13], v[48:63]
	s_waitcnt lgkmcnt(0)
	v_mfma_f32_32x32x16_bf16 v[64:79], v[236:239], v[244:247], v[64:79]
	v_mfma_f32_32x32x16_bf16 v[48:63], v[240:243], v[244:247], v[48:63]

.Lret_f_end:
	s_nop 3
	v_add_u32_e32 v1, v234, v207
	v_add_u32_e32 v10, 1, v1
	v_cvt_f32_i32_e32 v14, v10
	v_mul_f32_e32 v2, v232, v14
	v_exp_f32_e32 v4, v2
	v_lshlrev_b32_e32 v2, 3, v233
	v_mul_lo_u32 v3, v1, s68
	v_add3_u32 v5, v208, v2, v3
	v_mul_f32_e32 v2, v4, v96
	v_mul_f32_e32 v3, v4, v97
	v_cvt_pk_bf16_f32 v2, v2, v3
	v_mul_f32_e32 v3, v4, v98
	v_mul_f32_e32 v6, v4, v99
	v_cvt_pk_bf16_f32 v3, v3, v6
	v_add_u32_e32 v1, 33, v1
	ds_write_b64 v5, v[2:3] offset:34816
	v_mul_f32_e32 v2, v4, v100
	v_mul_f32_e32 v3, v4, v101
	v_cvt_f32_i32_e32 v1, v1
	v_cvt_pk_bf16_f32 v2, v2, v3
	v_mul_f32_e32 v3, v4, v102
	v_mul_f32_e32 v6, v4, v103
	v_cvt_pk_bf16_f32 v3, v3, v6
	ds_write_b64 v5, v[2:3] offset:34832
	v_mul_f32_e32 v2, v4, v104
	v_mul_f32_e32 v3, v4, v105
	v_cvt_pk_bf16_f32 v2, v2, v3
	v_mul_f32_e32 v3, v4, v106
	v_mul_f32_e32 v1, v232, v1
	v_mul_f32_e32 v6, v4, v107
	v_cvt_pk_bf16_f32 v3, v3, v6
	v_exp_f32_e32 v1, v1
	ds_write_b64 v5, v[2:3] offset:34848
	v_mul_f32_e32 v2, v4, v108
	v_mul_f32_e32 v3, v4, v109
	v_cvt_pk_bf16_f32 v2, v2, v3
	v_mul_f32_e32 v3, v4, v110
	v_mul_f32_e32 v4, v4, v111
	v_cvt_pk_bf16_f32 v3, v3, v4
	ds_write_b64 v5, v[2:3] offset:34864
	v_mul_f32_e32 v2, v1, v80
	v_mul_f32_e32 v3, v1, v81
	v_cvt_pk_bf16_f32 v2, v2, v3
	v_mul_f32_e32 v3, v1, v82
	v_mul_f32_e32 v4, v1, v83
	v_cvt_pk_bf16_f32 v3, v3, v4
	ds_write_b64 v5, v[2:3] offset:43520
	v_mul_f32_e32 v2, v1, v84
	v_mul_f32_e32 v3, v1, v85
	v_cvt_pk_bf16_f32 v2, v2, v3
	v_mul_f32_e32 v3, v1, v86
	v_mul_f32_e32 v4, v1, v87
	v_cvt_pk_bf16_f32 v3, v3, v4
	ds_write_b64 v5, v[2:3] offset:43536
	v_mul_f32_e32 v2, v1, v88
	v_mul_f32_e32 v3, v1, v89
	v_cvt_pk_bf16_f32 v2, v2, v3
	v_mul_f32_e32 v3, v1, v90
	s_add_u32 s16, s40, s28
	v_mul_f32_e32 v4, v1, v91
	v_cvt_pk_bf16_f32 v3, v3, v4
	s_addc_u32 s17, s41, s34
	ds_write_b64 v5, v[2:3] offset:43552
	v_mul_f32_e32 v2, v1, v92
	v_mul_f32_e32 v3, v1, v93
	s_lshl_b64 s[18:19], s[16:17], 12
	v_cvt_pk_bf16_f32 v2, v2, v3
	v_mul_f32_e32 v3, v1, v94
	s_or_b32 s18, s18, s80
	v_mul_f32_e32 v1, v1, v95
	v_cvt_pk_bf16_f32 v3, v3, v1
	s_add_u32 s56, s26, s18
	ds_write_b64 v5, v[2:3] offset:43568
	s_waitcnt lgkmcnt(0)
	s_barrier
	s_addc_u32 s57, s27, s19
	v_sub_u32_e32 v10, 0x7f, v197
	ds_read_b128 v[2:5], v228 offset:34816
	s_add_u32 s54, s64, s18
	v_cndmask_b32_e64 v1, v10, v197, s[44:45]
	s_addc_u32 s55, s65, s19
	s_lshl_b64 s[16:17], s[16:17], 5
	v_lshl_or_b32 v8, v1, 11, v203
	s_add_u32 s18, s78, s16
	v_ashrrev_i32_e32 v9, 31, v8
	s_addc_u32 s19, s79, s17
	v_lshl_add_u64 v[6:7], v[8:9], 1, s[56:57]
	s_mov_b64 s[16:17], -1
	s_and_b64 vcc, exec, s[46:47]
	v_mbcnt_hi_u32_b32 v1, -1, v226
	s_cbranch_vccz .LBB0_982
	global_load_dwordx4 v[12:15], v[6:7], off
	v_lshl_add_u64 v[8:9], v[8:9], 1, s[54:55]
	s_waitcnt lgkmcnt(0)
	v_lshlrev_b32_e32 v80, 16, v2
	v_and_b32_e32 v81, 0xffff0000, v2
	v_lshlrev_b32_e32 v82, 16, v3
	v_and_b32_e32 v83, 0xffff0000, v3
	v_lshlrev_b32_e32 v84, 16, v4
	v_and_b32_e32 v85, 0xffff0000, v4
	v_lshlrev_b32_e32 v86, 16, v5
	v_and_b32_e32 v87, 0xffff0000, v5
	s_waitcnt vmcnt(0)
	v_lshlrev_b32_e32 v88, 16, v12
	v_and_b32_e32 v89, 0xffff0000, v12
	v_lshlrev_b32_e32 v90, 16, v13
	v_and_b32_e32 v91, 0xffff0000, v13
	v_lshlrev_b32_e32 v92, 16, v14
	v_and_b32_e32 v93, 0xffff0000, v14
	v_lshlrev_b32_e32 v94, 16, v15
	v_and_b32_e32 v95, 0xffff0000, v15
	v_add_f32_e32 v80, v88, v80
	v_add_f32_e32 v81, v89, v81
	v_add_f32_e32 v82, v90, v82
	v_add_f32_e32 v83, v91, v83
	v_add_f32_e32 v84, v92, v84
	v_add_f32_e32 v85, v93, v85
	v_add_f32_e32 v86, v94, v86
	v_add_f32_e32 v87, v95, v87
	v_lshlrev_b32_e32 v94, 3, v10
	v_ashrrev_i32_e32 v95, 31, v94
	v_lshl_add_u64 v[94:95], v[94:95], 2, s[18:19]
	v_add_f32_e32 v88, v80, v81
	v_add_f32_e32 v89, v82, v83
	v_add_f32_e32 v90, v84, v85
	v_add_f32_e32 v91, v86, v87
	v_mul_f32_e32 v12, v80, v80
	v_mul_f32_e32 v13, v82, v82
	v_mul_f32_e32 v14, v84, v84
	v_mul_f32_e32 v15, v86, v86
	v_add_f32_e32 v88, v88, v89
	v_add_f32_e32 v90, v90, v91
	v_fmac_f32_e32 v12, v81, v81
	v_fmac_f32_e32 v13, v83, v83
	v_fmac_f32_e32 v14, v85, v85
	v_fmac_f32_e32 v15, v87, v87
	v_add_f32_e32 v92, v88, v90
	v_add_f32_e32 v12, v12, v13
	v_add_f32_e32 v14, v14, v15
	v_add_f32_e32 v93, v12, v14
	v_cvt_pk_bf16_f32 v80, v80, v81
	v_cvt_pk_bf16_f32 v81, v82, v83
	v_cvt_pk_bf16_f32 v82, v84, v85
	v_cvt_pk_bf16_f32 v83, v86, v87
	v_add_f32_dpp v92, v92, v92 quad_perm:[1,0,3,2] row_mask:0xf bank_mask:0xf
	v_add_f32_dpp v93, v93, v93 quad_perm:[1,0,3,2] row_mask:0xf bank_mask:0xf
	s_nop 0
	v_add_f32_dpp v92, v92, v92 quad_perm:[2,3,0,1] row_mask:0xf bank_mask:0xf
	v_add_f32_dpp v93, v93, v93 quad_perm:[2,3,0,1] row_mask:0xf bank_mask:0xf
	s_nop 0
	v_add_f32_dpp v92, v92, v92 row_ror:4 row_mask:0xf bank_mask:0xf
	v_add_f32_dpp v93, v93, v93 row_ror:4 row_mask:0xf bank_mask:0xf
	s_nop 0
	v_add_f32_dpp v92, v92, v92 row_ror:8 row_mask:0xf bank_mask:0xf
	v_add_f32_dpp v93, v93, v93 row_ror:8 row_mask:0xf bank_mask:0xf
	s_nop 0
	global_store_dwordx4 v[8:9], v[80:83], off
	s_and_saveexec_b64 s[16:17], s[8:9]
	s_cbranch_execz .LBB0_981
	global_atomic_add_f32 v[94:95], v92, off
	global_atomic_add_f32 v[94:95], v93, off offset:4

.LBB0_984:
	v_sub_u32_e32 v10, 0x5f, v197
	s_waitcnt lgkmcnt(0)
	v_cndmask_b32_e64 v2, v10, v231, s[44:45]
	v_lshl_or_b32 v8, v2, 11, v203
	ds_read_b128 v[2:5], v228 offset:43520
	v_ashrrev_i32_e32 v9, 31, v8
	v_cndmask_b32_e64 v11, 0, 1, s[46:47]
	v_lshl_add_u64 v[6:7], v[8:9], 1, s[56:57]
	v_cmp_ne_u32_e64 s[16:17], 1, v11
	s_andn2_b64 vcc, exec, s[46:47]
	s_mov_b64 s[58:59], -1
	s_cbranch_vccnz .LBB0_988
	global_load_dwordx4 v[12:15], v[6:7], off
	v_lshl_add_u64 v[8:9], v[8:9], 1, s[54:55]
	s_waitcnt lgkmcnt(0)
	v_lshlrev_b32_e32 v80, 16, v2
	v_and_b32_e32 v81, 0xffff0000, v2
	v_lshlrev_b32_e32 v82, 16, v3
	v_and_b32_e32 v83, 0xffff0000, v3
	v_lshlrev_b32_e32 v84, 16, v4
	v_and_b32_e32 v85, 0xffff0000, v4
	v_lshlrev_b32_e32 v86, 16, v5
	v_and_b32_e32 v87, 0xffff0000, v5
	s_waitcnt vmcnt(0)
	v_lshlrev_b32_e32 v88, 16, v12
	v_and_b32_e32 v89, 0xffff0000, v12
	v_lshlrev_b32_e32 v90, 16, v13
	v_and_b32_e32 v91, 0xffff0000, v13
	v_lshlrev_b32_e32 v92, 16, v14
	v_and_b32_e32 v93, 0xffff0000, v14
	v_lshlrev_b32_e32 v94, 16, v15
	v_and_b32_e32 v95, 0xffff0000, v15
	v_add_f32_e32 v80, v88, v80
	v_add_f32_e32 v81, v89, v81
	v_add_f32_e32 v82, v90, v82
	v_add_f32_e32 v83, v91, v83
	v_add_f32_e32 v84, v92, v84
	v_add_f32_e32 v85, v93, v85
	v_add_f32_e32 v86, v94, v86
	v_add_f32_e32 v87, v95, v87
	v_lshlrev_b32_e32 v94, 3, v10
	v_ashrrev_i32_e32 v95, 31, v94
	v_lshl_add_u64 v[94:95], v[94:95], 2, s[18:19]
	v_add_f32_e32 v88, v80, v81
	v_add_f32_e32 v89, v82, v83
	v_add_f32_e32 v90, v84, v85
	v_add_f32_e32 v91, v86, v87
	v_mul_f32_e32 v12, v80, v80
	v_mul_f32_e32 v13, v82, v82
	v_mul_f32_e32 v14, v84, v84
	v_mul_f32_e32 v15, v86, v86
	v_add_f32_e32 v88, v88, v89
	v_add_f32_e32 v90, v90, v91
	v_fmac_f32_e32 v12, v81, v81
	v_fmac_f32_e32 v13, v83, v83
	v_fmac_f32_e32 v14, v85, v85
	v_fmac_f32_e32 v15, v87, v87
	v_add_f32_e32 v92, v88, v90
	v_add_f32_e32 v12, v12, v13
	v_add_f32_e32 v14, v14, v15
	v_add_f32_e32 v93, v12, v14
	v_cvt_pk_bf16_f32 v80, v80, v81
	v_cvt_pk_bf16_f32 v81, v82, v83
	v_cvt_pk_bf16_f32 v82, v84, v85
	v_cvt_pk_bf16_f32 v83, v86, v87
	v_add_f32_dpp v92, v92, v92 quad_perm:[1,0,3,2] row_mask:0xf bank_mask:0xf
	v_add_f32_dpp v93, v93, v93 quad_perm:[1,0,3,2] row_mask:0xf bank_mask:0xf
	s_nop 0
	v_add_f32_dpp v92, v92, v92 quad_perm:[2,3,0,1] row_mask:0xf bank_mask:0xf
	v_add_f32_dpp v93, v93, v93 quad_perm:[2,3,0,1] row_mask:0xf bank_mask:0xf
	s_nop 0
	v_add_f32_dpp v92, v92, v92 row_ror:4 row_mask:0xf bank_mask:0xf
	v_add_f32_dpp v93, v93, v93 row_ror:4 row_mask:0xf bank_mask:0xf
	s_nop 0
	v_add_f32_dpp v92, v92, v92 row_ror:8 row_mask:0xf bank_mask:0xf
	v_add_f32_dpp v93, v93, v93 row_ror:8 row_mask:0xf bank_mask:0xf
	s_nop 0
	global_store_dwordx4 v[8:9], v[80:83], off
	s_and_saveexec_b64 s[58:59], s[8:9]
	s_cbranch_execz .LBB0_987
	global_atomic_add_f32 v[94:95], v92, off
	global_atomic_add_f32 v[94:95], v93, off offset:4

.LBB0_990:
	v_sub_u32_e32 v10, 63, v197
	s_waitcnt lgkmcnt(0)
	v_cndmask_b32_e64 v2, v10, v230, s[44:45]
	v_lshl_or_b32 v8, v2, 11, v203
	ds_read_b128 v[2:5], v228 offset:52224
	v_ashrrev_i32_e32 v9, 31, v8
	v_lshl_add_u64 v[6:7], v[8:9], 1, s[56:57]
	s_and_b64 vcc, exec, s[16:17]
	s_mov_b64 s[58:59], -1
	s_cbranch_vccnz .LBB0_994
	global_load_dwordx4 v[12:15], v[6:7], off
	v_lshl_add_u64 v[8:9], v[8:9], 1, s[54:55]
	s_waitcnt lgkmcnt(0)
	v_lshlrev_b32_e32 v80, 16, v2
	v_and_b32_e32 v81, 0xffff0000, v2
	v_lshlrev_b32_e32 v82, 16, v3
	v_and_b32_e32 v83, 0xffff0000, v3
	v_lshlrev_b32_e32 v84, 16, v4
	v_and_b32_e32 v85, 0xffff0000, v4
	v_lshlrev_b32_e32 v86, 16, v5
	v_and_b32_e32 v87, 0xffff0000, v5
	s_waitcnt vmcnt(0)
	v_lshlrev_b32_e32 v88, 16, v12
	v_and_b32_e32 v89, 0xffff0000, v12
	v_lshlrev_b32_e32 v90, 16, v13
	v_and_b32_e32 v91, 0xffff0000, v13
	v_lshlrev_b32_e32 v92, 16, v14
	v_and_b32_e32 v93, 0xffff0000, v14
	v_lshlrev_b32_e32 v94, 16, v15
	v_and_b32_e32 v95, 0xffff0000, v15
	v_add_f32_e32 v80, v88, v80
	v_add_f32_e32 v81, v89, v81
	v_add_f32_e32 v82, v90, v82
	v_add_f32_e32 v83, v91, v83
	v_add_f32_e32 v84, v92, v84
	v_add_f32_e32 v85, v93, v85
	v_add_f32_e32 v86, v94, v86
	v_add_f32_e32 v87, v95, v87
	v_lshlrev_b32_e32 v94, 3, v10
	v_ashrrev_i32_e32 v95, 31, v94
	v_lshl_add_u64 v[94:95], v[94:95], 2, s[18:19]
	v_add_f32_e32 v88, v80, v81
	v_add_f32_e32 v89, v82, v83
	v_add_f32_e32 v90, v84, v85
	v_add_f32_e32 v91, v86, v87
	v_mul_f32_e32 v12, v80, v80
	v_mul_f32_e32 v13, v82, v82
	v_mul_f32_e32 v14, v84, v84
	v_mul_f32_e32 v15, v86, v86
	v_add_f32_e32 v88, v88, v89
	v_add_f32_e32 v90, v90, v91
	v_fmac_f32_e32 v12, v81, v81
	v_fmac_f32_e32 v13, v83, v83
	v_fmac_f32_e32 v14, v85, v85
	v_fmac_f32_e32 v15, v87, v87
	v_add_f32_e32 v92, v88, v90
	v_add_f32_e32 v12, v12, v13
	v_add_f32_e32 v14, v14, v15
	v_add_f32_e32 v93, v12, v14
	v_cvt_pk_bf16_f32 v80, v80, v81
	v_cvt_pk_bf16_f32 v81, v82, v83
	v_cvt_pk_bf16_f32 v82, v84, v85
	v_cvt_pk_bf16_f32 v83, v86, v87
	v_add_f32_dpp v92, v92, v92 quad_perm:[1,0,3,2] row_mask:0xf bank_mask:0xf
	v_add_f32_dpp v93, v93, v93 quad_perm:[1,0,3,2] row_mask:0xf bank_mask:0xf
	s_nop 0
	v_add_f32_dpp v92, v92, v92 quad_perm:[2,3,0,1] row_mask:0xf bank_mask:0xf
	v_add_f32_dpp v93, v93, v93 quad_perm:[2,3,0,1] row_mask:0xf bank_mask:0xf
	s_nop 0
	v_add_f32_dpp v92, v92, v92 row_ror:4 row_mask:0xf bank_mask:0xf
	v_add_f32_dpp v93, v93, v93 row_ror:4 row_mask:0xf bank_mask:0xf
	s_nop 0
	v_add_f32_dpp v92, v92, v92 row_ror:8 row_mask:0xf bank_mask:0xf
	v_add_f32_dpp v93, v93, v93 row_ror:8 row_mask:0xf bank_mask:0xf
	s_nop 0
	global_store_dwordx4 v[8:9], v[80:83], off
	s_and_saveexec_b64 s[58:59], s[8:9]
	s_cbranch_execz .LBB0_993
	global_atomic_add_f32 v[94:95], v92, off
	global_atomic_add_f32 v[94:95], v93, off offset:4

.LBB0_996:
	v_sub_u32_e32 v10, 31, v197
	s_waitcnt lgkmcnt(0)
	v_cndmask_b32_e64 v2, v10, v229, s[44:45]
	v_lshl_or_b32 v8, v2, 11, v203
	ds_read_b128 v[2:5], v228 offset:60928
	v_ashrrev_i32_e32 v9, 31, v8
	v_lshl_add_u64 v[6:7], v[8:9], 1, s[56:57]
	s_and_b64 vcc, exec, s[16:17]
	s_mov_b64 s[16:17], -1
	s_cbranch_vccnz .LBB0_1000
	global_load_dwordx4 v[12:15], v[6:7], off
	v_lshl_add_u64 v[8:9], v[8:9], 1, s[54:55]
	s_waitcnt lgkmcnt(0)
	v_lshlrev_b32_e32 v80, 16, v2
	v_and_b32_e32 v81, 0xffff0000, v2
	v_lshlrev_b32_e32 v82, 16, v3
	v_and_b32_e32 v83, 0xffff0000, v3
	v_lshlrev_b32_e32 v84, 16, v4
	v_and_b32_e32 v85, 0xffff0000, v4
	v_lshlrev_b32_e32 v86, 16, v5
	v_and_b32_e32 v87, 0xffff0000, v5
	s_waitcnt vmcnt(0)
	v_lshlrev_b32_e32 v88, 16, v12
	v_and_b32_e32 v89, 0xffff0000, v12
	v_lshlrev_b32_e32 v90, 16, v13
	v_and_b32_e32 v91, 0xffff0000, v13
	v_lshlrev_b32_e32 v92, 16, v14
	v_and_b32_e32 v93, 0xffff0000, v14
	v_lshlrev_b32_e32 v94, 16, v15
	v_and_b32_e32 v95, 0xffff0000, v15
	v_add_f32_e32 v80, v88, v80
	v_add_f32_e32 v81, v89, v81
	v_add_f32_e32 v82, v90, v82
	v_add_f32_e32 v83, v91, v83
	v_add_f32_e32 v84, v92, v84
	v_add_f32_e32 v85, v93, v85
	v_add_f32_e32 v86, v94, v86
	v_add_f32_e32 v87, v95, v87
	v_lshlrev_b32_e32 v94, 3, v10
	v_ashrrev_i32_e32 v95, 31, v94
	v_lshl_add_u64 v[94:95], v[94:95], 2, s[18:19]
	v_add_f32_e32 v88, v80, v81
	v_add_f32_e32 v89, v82, v83
	v_add_f32_e32 v90, v84, v85
	v_add_f32_e32 v91, v86, v87
	v_mul_f32_e32 v12, v80, v80
	v_mul_f32_e32 v13, v82, v82
	v_mul_f32_e32 v14, v84, v84
	v_mul_f32_e32 v15, v86, v86
	v_add_f32_e32 v88, v88, v89
	v_add_f32_e32 v90, v90, v91
	v_fmac_f32_e32 v12, v81, v81
	v_fmac_f32_e32 v13, v83, v83
	v_fmac_f32_e32 v14, v85, v85
	v_fmac_f32_e32 v15, v87, v87
	v_add_f32_e32 v92, v88, v90
	v_add_f32_e32 v12, v12, v13
	v_add_f32_e32 v14, v14, v15
	v_add_f32_e32 v93, v12, v14
	v_cvt_pk_bf16_f32 v80, v80, v81
	v_cvt_pk_bf16_f32 v81, v82, v83
	v_cvt_pk_bf16_f32 v82, v84, v85
	v_cvt_pk_bf16_f32 v83, v86, v87
	v_add_f32_dpp v92, v92, v92 quad_perm:[1,0,3,2] row_mask:0xf bank_mask:0xf
	v_add_f32_dpp v93, v93, v93 quad_perm:[1,0,3,2] row_mask:0xf bank_mask:0xf
	s_nop 0
	v_add_f32_dpp v92, v92, v92 quad_perm:[2,3,0,1] row_mask:0xf bank_mask:0xf
	v_add_f32_dpp v93, v93, v93 quad_perm:[2,3,0,1] row_mask:0xf bank_mask:0xf
	s_nop 0
	v_add_f32_dpp v92, v92, v92 row_ror:4 row_mask:0xf bank_mask:0xf
	v_add_f32_dpp v93, v93, v93 row_ror:4 row_mask:0xf bank_mask:0xf
	s_nop 0
	v_add_f32_dpp v92, v92, v92 row_ror:8 row_mask:0xf bank_mask:0xf
	v_add_f32_dpp v93, v93, v93 row_ror:8 row_mask:0xf bank_mask:0xf
	s_nop 0
	global_store_dwordx4 v[8:9], v[80:83], off
	s_and_saveexec_b64 s[16:17], s[8:9]
	s_cbranch_execz .LBB0_999
	global_atomic_add_f32 v[94:95], v92, off
	global_atomic_add_f32 v[94:95], v93, off offset:4
